# phase 3 gMLP items: proj0 u/v/z tile loads marked nt (read once)
# speedup vs baseline: 1.0239x; 1.0077x over previous
.LBB0_401:
	s_and_b32 s0, s53, 0xffffff80
	s_and_b32 s6, s91, 3
	v_add_u32_e32 v166, s0, v187
	v_mov_b64_e32 v[0:1], s[22:23]
	v_lshl_or_b32 v150, s6, 15, v205
	v_mad_i64_i32 v[0:1], s[0:1], v166, s62, v[0:1]
	s_lshl_b32 s12, s6, 9
	v_lshl_add_u64 v[36:37], v[152:153], 0, v[150:151]
	v_lshl_add_u64 v[0:1], v[0:1], 0, s[12:13]
	v_lshlrev_b32_e32 v150, 1, v148
	v_lshl_add_u64 v[96:97], v[0:1], 0, v[150:151]
	v_add_co_u32_e32 v0, vcc, s72, v96
	global_load_dwordx4 v[4:7], v[96:97], off offset:2048 nt
	s_nop 0
	v_addc_co_u32_e32 v1, vcc, 0, v97, vcc
	v_add_co_u32_e32 v2, vcc, s73, v96
	s_nop 1
	v_addc_co_u32_e32 v3, vcc, 0, v97, vcc
	global_load_dwordx4 v[8:11], v[0:1], off offset:2048 nt
	global_load_dwordx4 v[12:15], v[2:3], off offset:2048 nt
	v_add_co_u32_e32 v0, vcc, s74, v96
	s_nop 1
	v_addc_co_u32_e32 v1, vcc, 0, v97, vcc
	v_add_co_u32_e32 v2, vcc, s75, v96
	s_nop 1
	v_addc_co_u32_e32 v3, vcc, 0, v97, vcc
	global_load_dwordx4 v[16:19], v[0:1], off offset:2048 nt
	global_load_dwordx4 v[20:23], v[2:3], off offset:2048 nt
	v_add_co_u32_e32 v0, vcc, s76, v96
	s_nop 1
	v_addc_co_u32_e32 v1, vcc, 0, v97, vcc
	v_add_co_u32_e32 v2, vcc, s77, v96
	s_nop 1
	v_addc_co_u32_e32 v3, vcc, 0, v97, vcc
	global_load_dwordx4 v[24:27], v[0:1], off offset:2048 nt
	global_load_dwordx4 v[28:31], v[2:3], off offset:2048 nt
	v_add_co_u32_e32 v0, vcc, s78, v96
	s_nop 1
	v_addc_co_u32_e32 v1, vcc, 0, v97, vcc
	global_load_dwordx4 v[32:35], v[0:1], off offset:2048 nt
	s_nop 0
	global_load_dwordx4 v[0:3], v[36:37], off
	global_load_dwordx4 v[88:91], v[36:37], off offset:1024
	global_load_dwordx4 v[80:83], v[36:37], off offset:2048
	global_load_dwordx4 v[144:147], v[36:37], off offset:3072
	v_add_co_u32_e32 v36, vcc, 0x1000, v36
	s_nop 1
	v_addc_co_u32_e32 v37, vcc, 0, v37, vcc
	v_add_co_u32_e32 v98, vcc, s80, v96
	global_load_dwordx4 v[140:143], v[36:37], off
	global_load_dwordx4 v[136:139], v[36:37], off offset:1024
	global_load_dwordx4 v[132:135], v[36:37], off offset:2048
	global_load_dwordx4 v[128:131], v[36:37], off offset:3072
	global_load_dwordx4 v[108:111], v[96:97], off nt
	v_addc_co_u32_e32 v99, vcc, 0, v97, vcc
	v_add_co_u32_e32 v104, vcc, s81, v96
	s_nop 1
	v_addc_co_u32_e32 v105, vcc, 0, v97, vcc
	v_add_co_u32_e32 v106, vcc, s82, v96
	s_nop 1
	v_addc_co_u32_e32 v107, vcc, 0, v97, vcc
	v_add_co_u32_e32 v168, vcc, s83, v96
	global_load_dwordx4 v[100:103], v[98:99], off offset:-4096 nt
	global_load_dwordx4 v[92:95], v[104:105], off offset:-4096 nt
	global_load_dwordx4 v[84:87], v[106:107], off offset:-4096 nt
	v_addc_co_u32_e32 v169, vcc, 0, v97, vcc
	v_add_co_u32_e32 v170, vcc, s84, v96
	s_waitcnt vmcnt(19)
	ds_write_b128 v189, v[4:7]
	s_waitcnt vmcnt(18)
	ds_write_b128 v191, v[8:11]
	s_waitcnt vmcnt(17)
	ds_write_b128 v192, v[12:15]
	s_waitcnt vmcnt(16)
	ds_write_b128 v193, v[16:19]
	s_waitcnt vmcnt(15)
	ds_write_b128 v194, v[20:23]
	s_waitcnt vmcnt(14)
	ds_write_b128 v195, v[24:27]
	s_waitcnt vmcnt(13)
	ds_write_b128 v196, v[28:31]
	s_waitcnt vmcnt(12)
	ds_write_b128 v197, v[32:35]
	v_addc_co_u32_e32 v171, vcc, 0, v97, vcc
	v_add_co_u32_e32 v172, vcc, s85, v96
	global_load_dwordx4 v[76:79], v[168:169], off offset:-4096 nt
	global_load_dwordx4 v[72:75], v[170:171], off offset:-4096 nt
	v_addc_co_u32_e32 v173, vcc, 0, v97, vcc
	v_add_co_u32_e32 v174, vcc, s86, v96
	s_nop 1
	v_addc_co_u32_e32 v175, vcc, 0, v97, vcc
	global_load_dwordx4 v[68:71], v[172:173], off offset:-4096 nt
	global_load_dwordx4 v[64:67], v[174:175], off offset:-4096 nt
	s_waitcnt lgkmcnt(0)
	s_barrier
	ds_read_b128 v[4:7], v206
	ds_read_b128 v[20:23], v207
	ds_read_b128 v[24:27], v208
	ds_read_b128 v[52:55], v209
	ds_read_b128 v[32:35], v210
	ds_read_b128 v[44:47], v211
	s_waitcnt lgkmcnt(4)
	v_and_b32_e32 v11, 0xffff0000, v20
	v_lshlrev_b32_e32 v10, 16, v20
	v_lshlrev_b32_e32 v8, 16, v21
	s_waitcnt lgkmcnt(1)
	v_and_b32_e32 v29, 0xffff0000, v34
	v_and_b32_e32 v28, 0xffff0000, v32
	v_and_b32_e32 v31, 0xffff0000, v35
	v_and_b32_e32 v30, 0xffff0000, v33
	v_lshlrev_b32_e32 v43, 16, v34
	v_lshlrev_b32_e32 v42, 16, v32
	v_lshlrev_b32_e32 v41, 16, v35
	v_lshlrev_b32_e32 v40, 16, v33
	v_pk_mul_f32 v[32:33], v[28:29], v[28:29]
	v_pk_mul_f32 v[34:35], v[30:31], v[30:31]
	v_pk_fma_f32 v[32:33], v[42:43], v[42:43], v[32:33]
	v_pk_fma_f32 v[34:35], v[40:41], v[40:41], v[34:35]
	s_waitcnt lgkmcnt(0)
	v_lshlrev_b32_e32 v37, 16, v46
	v_pk_add_f32 v[32:33], v[32:33], v[34:35]
	v_lshlrev_b32_e32 v36, 16, v44
	v_pk_add_f32 v[116:117], v[32:33], v[32:33] op_sel:[0,1] op_sel_hi:[1,0]
	v_and_b32_e32 v33, 0xffff0000, v46
	v_and_b32_e32 v32, 0xffff0000, v44
	v_lshlrev_b32_e32 v39, 16, v47
	v_lshlrev_b32_e32 v38, 16, v45
	v_and_b32_e32 v35, 0xffff0000, v47
	v_and_b32_e32 v34, 0xffff0000, v45
	v_pk_add_f32 v[44:45], v[36:37], v[32:33]
	v_pk_add_f32 v[46:47], v[38:39], v[34:35]
	v_and_b32_e32 v9, 0xffff0000, v21
	v_pk_add_f32 v[44:45], v[44:45], v[46:47]
	v_mov_b32_e32 v46, v32
	v_mov_b32_e32 v47, v34
	v_pk_add_f32 v[218:219], v[44:45], v[44:45] op_sel:[0,1] op_sel_hi:[1,0]
	v_mov_b32_e32 v44, v36
	v_mov_b32_e32 v45, v38
	v_pk_mul_f32 v[46:47], v[46:47], v[46:47]
	v_mul_f32_e32 v20, v11, v11
	v_pk_fma_f32 v[44:45], v[44:45], v[44:45], v[46:47]
	ds_read_b128 v[46:49], v212
	ds_read_b128 v[180:183], v213
	v_lshlrev_b32_e32 v12, 16, v4
	v_and_b32_e32 v13, 0xffff0000, v4
	v_lshlrev_b32_e32 v14, 16, v5
	v_and_b32_e32 v15, 0xffff0000, v5
	v_lshlrev_b32_e32 v16, 16, v6
	v_and_b32_e32 v17, 0xffff0000, v6
	v_lshlrev_b32_e32 v18, 16, v7
	v_and_b32_e32 v19, 0xffff0000, v7
	v_lshlrev_b32_e32 v6, 16, v22
	v_and_b32_e32 v7, 0xffff0000, v22
	v_lshlrev_b32_e32 v4, 16, v23
	v_and_b32_e32 v5, 0xffff0000, v23
	v_pk_fma_f32 v[118:119], v[10:11], v[10:11], v[20:21] op_sel_hi:[1,1,0]
	v_mov_b32_e32 v20, v10
	v_mov_b32_e32 v21, v8
	v_mov_b32_e32 v22, v11
	v_mov_b32_e32 v23, v9
	v_pk_add_f32 v[20:21], v[20:21], v[22:23]
	v_mov_b32_e32 v50, v33
	v_mov_b32_e32 v51, v35
	v_pk_add_f32 v[178:179], v[20:21], v[20:21] op_sel:[0,1] op_sel_hi:[1,0]
	v_mul_f32_e32 v20, v9, v9
	v_pk_add_f32 v[122:123], v[44:45], v[44:45] op_sel:[0,1] op_sel_hi:[1,0]
	v_mov_b32_e32 v44, v37
	v_mov_b32_e32 v45, v39
	v_pk_mul_f32 v[50:51], v[50:51], v[50:51]
	v_pk_fma_f32 v[120:121], v[8:9], v[8:9], v[20:21] op_sel_hi:[1,1,0]
	v_mul_f32_e32 v20, v7, v7
	v_pk_fma_f32 v[44:45], v[44:45], v[44:45], v[50:51]
	v_mov_b32_e32 v238, v14
	v_mov_b32_e32 v239, v18
	v_mov_b32_e32 v240, v15
	v_mov_b32_e32 v241, v19
	v_pk_fma_f32 v[126:127], v[6:7], v[6:7], v[20:21] op_sel_hi:[1,1,0]
	v_mov_b32_e32 v20, v6
	v_mov_b32_e32 v21, v4
	v_mov_b32_e32 v22, v7
	v_mov_b32_e32 v23, v5
	v_pk_add_f32 v[124:125], v[44:45], v[44:45] op_sel:[0,1] op_sel_hi:[1,0]
	s_waitcnt lgkmcnt(1)
	v_lshlrev_b32_e32 v45, 16, v47
	v_lshlrev_b32_e32 v44, 16, v46
	v_and_b32_e32 v47, 0xffff0000, v47
	v_and_b32_e32 v46, 0xffff0000, v46
	v_pk_add_f32 v[238:239], v[238:239], v[240:241]
	v_mov_b32_e32 v240, v12
	v_mov_b32_e32 v241, v16
	v_mov_b32_e32 v242, v13
	v_mov_b32_e32 v243, v17
	v_pk_add_f32 v[20:21], v[20:21], v[22:23]
	v_pk_add_f32 v[50:51], v[44:45], v[46:47]
	v_pk_add_f32 v[240:241], v[240:241], v[242:243]
	v_pk_add_f32 v[184:185], v[20:21], v[20:21] op_sel:[0,1] op_sel_hi:[1,0]
	v_pk_add_f32 v[220:221], v[50:51], v[50:51] op_sel:[0,1] op_sel_hi:[1,0]
	v_lshlrev_b32_e32 v59, 16, v49
	v_lshlrev_b32_e32 v58, 16, v48
	v_and_b32_e32 v51, 0xffff0000, v49
	v_and_b32_e32 v50, 0xffff0000, v48
	v_mov_b32_e32 v56, v44
	v_mov_b32_e32 v57, v46
	v_mul_f32_e32 v44, v46, v46
	v_pk_add_f32 v[238:239], v[240:241], v[238:239]
	v_pk_add_f32 v[48:49], v[58:59], v[50:51]
	v_pk_fma_f32 v[224:225], v[56:57], v[56:57], v[44:45] op_sel_hi:[1,1,0]
	v_mov_b32_e32 v46, v45
	v_mul_f32_e32 v44, v47, v47
	v_and_b32_e32 v119, 64, v216
	v_pk_add_f32 v[238:239], v[238:239], v[238:239] op_sel:[0,1] op_sel_hi:[1,0]
	v_mov_b32_e32 v179, v40
	v_mov_b32_e32 v185, v30
	v_mul_f32_e32 v20, v5, v5
	v_pk_add_f32 v[222:223], v[48:49], v[48:49] op_sel:[0,1] op_sel_hi:[1,0]
	v_pk_fma_f32 v[226:227], v[46:47], v[46:47], v[44:45] op_sel_hi:[1,1,0]
	v_mov_b32_e32 v114, v58
	v_mov_b32_e32 v115, v50
	v_mul_f32_e32 v44, v50, v50
	v_mov_b32_e32 v50, v59
	v_lshlrev_b32_e32 v58, 16, v52
	v_and_b32_e32 v59, 0xffff0000, v52
	v_lshlrev_b32_e32 v62, 16, v54
	v_and_b32_e32 v63, 0xffff0000, v54
	s_waitcnt lgkmcnt(0)
	v_lshlrev_b32_e32 v52, 16, v181
	v_and_b32_e32 v54, 0xffff0000, v181
	v_xor_b32_e32 v117, 1, v216
	v_add_u32_e32 v119, 64, v119
	v_pk_add_f32 v[178:179], v[178:179], v[184:185]
	v_mov_b32_e32 v239, v42
	v_mov_b32_e32 v184, v151
	v_mov_b32_e32 v185, v28
	v_pk_fma_f32 v[176:177], v[4:5], v[4:5], v[20:21] op_sel_hi:[1,1,0]
	v_lshlrev_b32_e32 v20, 16, v24
	v_and_b32_e32 v21, 0xffff0000, v24
	v_lshlrev_b32_e32 v22, 16, v25
	v_and_b32_e32 v23, 0xffff0000, v25
	v_lshlrev_b32_e32 v24, 16, v26
	v_and_b32_e32 v25, 0xffff0000, v26
	v_lshlrev_b32_e32 v26, 16, v27
	v_and_b32_e32 v27, 0xffff0000, v27
	v_pk_fma_f32 v[228:229], v[114:115], v[114:115], v[44:45] op_sel_hi:[1,1,0]
	v_mul_f32_e32 v44, v51, v51
	v_lshlrev_b32_e32 v112, 16, v55
	v_and_b32_e32 v113, 0xffff0000, v55
	v_and_b32_e32 v49, 0xffff0000, v182
	v_and_b32_e32 v48, 0xffff0000, v180
	v_and_b32_e32 v55, 0xffff0000, v183
	v_cmp_lt_i32_e32 vcc, v117, v119
	v_pk_add_f32 v[184:185], v[238:239], v[184:185]
	v_mov_b32_e32 v221, v52
	v_mov_b32_e32 v223, v54
	v_pk_fma_f32 v[230:231], v[50:51], v[50:51], v[44:45] op_sel_hi:[1,1,0]
	v_lshlrev_b32_e32 v60, 16, v53
	v_and_b32_e32 v61, 0xffff0000, v53
	v_lshlrev_b32_e32 v45, 16, v182
	v_lshlrev_b32_e32 v44, 16, v180
	v_lshlrev_b32_e32 v53, 16, v183
	v_pk_mul_f32 v[180:181], v[48:49], v[48:49]
	v_pk_mul_f32 v[182:183], v[54:55], v[54:55]
	v_cndmask_b32_e32 v117, v216, v117, vcc
	v_pk_add_f32 v[178:179], v[184:185], v[178:179]
	v_pk_add_f32 v[184:185], v[220:221], v[222:223]
	v_pk_mul_f32 v[222:223], v[26:27], v[26:27]
	v_pk_fma_f32 v[180:181], v[44:45], v[44:45], v[180:181]
	v_pk_fma_f32 v[182:183], v[52:53], v[52:53], v[182:183]
	v_lshlrev_b32_e32 v165, 2, v117
	v_xor_b32_e32 v117, 2, v216
	v_mov_b32_e32 v127, v222
	v_mov_b32_e32 v177, v223
	v_pk_mul_f32 v[222:223], v[24:25], v[24:25]
	v_pk_add_f32 v[180:181], v[180:181], v[182:183]
	v_cmp_lt_i32_e32 vcc, v117, v119
	v_mul_f32_e32 v182, v19, v19
	v_mul_f32_e32 v232, v17, v17
	v_add_f32_e32 v220, v27, v26
	v_pk_add_f32 v[126:127], v[126:127], v[176:177]
	v_mov_b32_e32 v221, v31
	v_add_f32_e32 v176, v25, v24
	v_mov_b32_e32 v119, v222
	v_mov_b32_e32 v121, v223
	v_mov_b32_e32 v177, v41
	v_pk_fma_f32 v[182:183], v[18:19], v[18:19], v[182:183] op_sel_hi:[1,1,0]
	v_pk_fma_f32 v[232:233], v[16:17], v[16:17], v[232:233] op_sel_hi:[1,1,0]
	v_pk_add_f32 v[118:119], v[118:119], v[120:121]
	v_pk_add_f32 v[120:121], v[176:177], v[220:221]
	v_pk_mul_f32 v[176:177], v[22:23], v[22:23]
	v_pk_add_f32 v[118:119], v[118:119], v[126:127]
	v_mov_b32_e32 v233, v176
	v_mov_b32_e32 v183, v177
	v_add_f32_e32 v126, v23, v22
	v_pk_add_f32 v[176:177], v[232:233], v[182:183]
	v_mov_b32_e32 v127, v29
	v_add_f32_e32 v182, v21, v20
	v_mov_b32_e32 v183, v43
	v_pk_add_f32 v[126:127], v[182:183], v[126:127]
	v_mul_f32_e32 v234, v15, v15
	v_pk_add_f32 v[120:121], v[126:127], v[120:121]
	v_mul_f32_e32 v236, v13, v13
	v_pk_add_f32 v[120:121], v[178:179], v[120:121]
	v_mov_b32_e32 v219, v48
	v_pk_add_f32 v[120:121], v[120:121], v[120:121] op_sel:[0,1] op_sel_hi:[1,0]
	v_pk_fma_f32 v[234:235], v[14:15], v[14:15], v[234:235] op_sel_hi:[1,1,0]
	v_mov_b32_e32 v121, v44
	v_pk_fma_f32 v[236:237], v[12:13], v[12:13], v[236:237] op_sel_hi:[1,1,0]
	v_pk_mul_f32 v[220:221], v[20:21], v[20:21]
	v_pk_add_f32 v[120:121], v[120:121], v[218:219]
	v_mov_b32_e32 v237, v220
	v_mov_b32_e32 v235, v221
	v_pk_add_f32 v[120:121], v[120:121], v[184:185]
	v_pk_mul_f32 v[178:179], v[112:113], v[112:113]
	v_pk_mul_f32 v[184:185], v[62:63], v[62:63]
	v_pk_add_f32 v[220:221], v[236:237], v[234:235]
	v_mov_b32_e32 v229, v178
	v_mov_b32_e32 v231, v179
	v_mov_b32_e32 v225, v184
	v_mov_b32_e32 v227, v185
	v_pk_add_f32 v[176:177], v[220:221], v[176:177]
	v_pk_add_f32 v[178:179], v[228:229], v[230:231]
	v_pk_add_f32 v[184:185], v[224:225], v[226:227]
	v_pk_add_f32 v[118:119], v[176:177], v[118:119]
	v_pk_add_f32 v[178:179], v[184:185], v[178:179]
	v_pk_mul_f32 v[184:185], v[60:61], v[60:61]
	v_cndmask_b32_e32 v117, v216, v117, vcc
	v_pk_add_f32 v[118:119], v[118:119], v[118:119] op_sel:[0,1] op_sel_hi:[1,0]
	v_mov_b32_e32 v123, v184
	v_mov_b32_e32 v125, v185
	v_pk_mul_f32 v[184:185], v[58:59], v[58:59]
	v_lshlrev_b32_e32 v167, 2, v117
	v_add_f32_e32 v176, v113, v112
	v_mov_b32_e32 v177, v55
	v_add_f32_e32 v182, v63, v62
	v_mov_b32_e32 v183, v53
	v_mov_b32_e32 v117, v185
	v_mov_b32_e32 v119, v184
	v_pk_add_f32 v[176:177], v[182:183], v[176:177]
	v_add_f32_e32 v182, v61, v60
	v_pk_add_f32 v[122:123], v[122:123], v[124:125]
	v_mov_b32_e32 v183, v49
	v_add_f32_e32 v124, v59, v58
	v_mov_b32_e32 v125, v45
	v_pk_add_f32 v[116:117], v[118:119], v[116:117]
	v_pk_add_f32 v[118:119], v[124:125], v[182:183]
	v_pk_add_f32 v[116:117], v[116:117], v[122:123]
	v_pk_add_f32 v[118:119], v[118:119], v[176:177]
	v_pk_add_f32 v[116:117], v[116:117], v[178:179]
	v_pk_add_f32 v[180:181], v[180:181], v[180:181] op_sel:[0,1] op_sel_hi:[1,0]
	v_pk_add_f32 v[118:119], v[120:121], v[118:119]
	v_pk_add_f32 v[116:117], v[116:117], v[116:117] op_sel:[0,1] op_sel_hi:[1,0]
	v_mov_b32_e32 v181, v119
	v_mov_b32_e32 v117, v118
	v_pk_add_f32 v[116:117], v[116:117], v[180:181]
	ds_bpermute_b32 v119, v165, v117
	ds_bpermute_b32 v118, v165, v116
	v_mov_b32_e32 v126, v42
	v_mov_b32_e32 v127, v28
	v_mov_b32_e32 v28, v43
	v_mov_b32_e32 v121, v30
	s_waitcnt lgkmcnt(0)
	v_pk_add_f32 v[42:43], v[116:117], v[118:119]
	ds_bpermute_b32 v117, v167, v43
	ds_bpermute_b32 v116, v167, v42
	v_mov_b32_e32 v30, v41
	v_mov_b32_e32 v41, v32
	v_mov_b32_e32 v120, v40
	v_mov_b32_e32 v40, v36
	s_waitcnt lgkmcnt(0)
	v_pk_add_f32 v[42:43], v[42:43], v[116:117]
	v_mov_b32_e32 v118, v38
	v_pk_mul_f32 v[42:43], v[42:43], s[54:55] op_sel_hi:[1,0]
	v_mov_b32_e32 v119, v34
	v_fma_f32 v32, -v43, v43, v42
	v_max_f32_e32 v32, 0, v32
	v_add_f32_e32 v32, 0x3727c5ac, v32
	v_mul_f32_e32 v36, 0x4b800000, v32
	v_cmp_gt_f32_e32 vcc, s79, v32
	v_mov_b32_e32 v34, v39
	v_add_u32_e32 v167, v199, v200
	v_cndmask_b32_e32 v32, v32, v36, vcc
	v_rsq_f32_e32 v36, v32
	v_mov_b32_e32 v32, v37
	v_add_u32_e32 v165, v198, v200
	v_add_u32_e32 v177, v199, v201
	v_mul_f32_e32 v37, 0x45800000, v36
	v_cndmask_b32_e32 v36, v36, v37, vcc
	v_mul_f32_e64 v38, v36, -v43
	v_pk_fma_f32 v[12:13], v[36:37], v[12:13], v[38:39] op_sel_hi:[0,1,0]
	v_pk_fma_f32 v[14:15], v[36:37], v[14:15], v[38:39] op_sel_hi:[0,1,0]
	v_cvt_pk_bf16_f32 v12, v12, v13
	v_cvt_pk_bf16_f32 v13, v14, v15
	v_pk_fma_f32 v[14:15], v[36:37], v[16:17], v[38:39] op_sel_hi:[0,1,0]
	v_pk_fma_f32 v[16:17], v[36:37], v[18:19], v[38:39] op_sel_hi:[0,1,0]
	v_cvt_pk_bf16_f32 v14, v14, v15
	v_cvt_pk_bf16_f32 v15, v16, v17
	v_pk_fma_f32 v[6:7], v[36:37], v[6:7], v[38:39] op_sel_hi:[0,1,0]
	v_pk_fma_f32 v[4:5], v[36:37], v[4:5], v[38:39] op_sel_hi:[0,1,0]
	ds_write_b128 v206, v[12:15]
	v_pk_fma_f32 v[10:11], v[36:37], v[10:11], v[38:39] op_sel_hi:[0,1,0]
	v_pk_fma_f32 v[8:9], v[36:37], v[8:9], v[38:39] op_sel_hi:[0,1,0]
	v_cvt_pk_bf16_f32 v12, v6, v7
	v_cvt_pk_bf16_f32 v13, v4, v5
	v_pk_fma_f32 v[4:5], v[36:37], v[20:21], v[38:39] op_sel_hi:[0,1,0]
	v_pk_fma_f32 v[6:7], v[36:37], v[22:23], v[38:39] op_sel_hi:[0,1,0]
	v_cvt_pk_bf16_f32 v10, v10, v11
	v_cvt_pk_bf16_f32 v11, v8, v9
	v_cvt_pk_bf16_f32 v4, v4, v5
	v_cvt_pk_bf16_f32 v5, v6, v7
	v_pk_fma_f32 v[6:7], v[36:37], v[24:25], v[38:39] op_sel_hi:[0,1,0]
	v_pk_fma_f32 v[8:9], v[36:37], v[26:27], v[38:39] op_sel_hi:[0,1,0]
	v_cvt_pk_bf16_f32 v6, v6, v7
	v_cvt_pk_bf16_f32 v7, v8, v9
	ds_write_b128 v208, v[4:7]
	v_pk_fma_f32 v[4:5], v[36:37], v[126:127], v[38:39] op_sel_hi:[0,1,0]
	v_pk_fma_f32 v[6:7], v[36:37], v[120:121], v[38:39] op_sel_hi:[0,1,0]
	v_cvt_pk_bf16_f32 v4, v4, v5
	v_cvt_pk_bf16_f32 v5, v6, v7
	v_pk_fma_f32 v[6:7], v[36:37], v[28:29], v[38:39] op_sel_hi:[0,1,0]
	v_pk_fma_f32 v[8:9], v[36:37], v[30:31], v[38:39] op_sel_hi:[0,1,0]
	v_cvt_pk_bf16_f32 v6, v6, v7
	v_cvt_pk_bf16_f32 v7, v8, v9
	ds_write_b128 v210, v[4:7]
	v_pk_fma_f32 v[4:5], v[36:37], v[40:41], v[38:39] op_sel_hi:[0,1,0]
	v_pk_fma_f32 v[6:7], v[36:37], v[118:119], v[38:39] op_sel_hi:[0,1,0]
	v_cvt_pk_bf16_f32 v4, v4, v5
	v_cvt_pk_bf16_f32 v5, v6, v7
	v_pk_fma_f32 v[6:7], v[36:37], v[32:33], v[38:39] op_sel_hi:[0,1,0]
	v_pk_fma_f32 v[8:9], v[36:37], v[34:35], v[38:39] op_sel_hi:[0,1,0]
	v_cvt_pk_bf16_f32 v6, v6, v7
	v_cvt_pk_bf16_f32 v7, v8, v9
	ds_write_b128 v211, v[4:7]
	v_pk_fma_f32 v[4:5], v[36:37], v[56:57], v[38:39] op_sel_hi:[0,1,0]
	v_pk_fma_f32 v[6:7], v[36:37], v[46:47], v[38:39] op_sel_hi:[0,1,0]
	v_cvt_pk_bf16_f32 v4, v4, v5
	v_cvt_pk_bf16_f32 v5, v6, v7
	v_pk_fma_f32 v[6:7], v[36:37], v[114:115], v[38:39] op_sel_hi:[0,1,0]
	v_pk_fma_f32 v[8:9], v[36:37], v[50:51], v[38:39] op_sel_hi:[0,1,0]
	v_cvt_pk_bf16_f32 v6, v6, v7
	v_cvt_pk_bf16_f32 v7, v8, v9
	ds_write_b128 v212, v[4:7]
	v_pk_fma_f32 v[4:5], v[36:37], v[58:59], v[38:39] op_sel_hi:[0,1,0]
	v_pk_fma_f32 v[6:7], v[36:37], v[60:61], v[38:39] op_sel_hi:[0,1,0]
	v_cvt_pk_bf16_f32 v4, v4, v5
	v_cvt_pk_bf16_f32 v5, v6, v7
	v_pk_fma_f32 v[6:7], v[36:37], v[62:63], v[38:39] op_sel_hi:[0,1,0]
	v_pk_fma_f32 v[8:9], v[36:37], v[112:113], v[38:39] op_sel_hi:[0,1,0]
	v_cvt_pk_bf16_f32 v6, v6, v7
	v_cvt_pk_bf16_f32 v7, v8, v9
	ds_write_b128 v209, v[4:7]
	v_mov_b32_e32 v4, v44
	v_mov_b32_e32 v5, v48
	v_mov_b32_e32 v6, v52
	v_mov_b32_e32 v7, v54
	v_pk_fma_f32 v[4:5], v[36:37], v[4:5], v[38:39] op_sel_hi:[0,1,0]
	v_pk_fma_f32 v[6:7], v[36:37], v[6:7], v[38:39] op_sel_hi:[0,1,0]
	v_mov_b32_e32 v48, v45
	v_mov_b32_e32 v54, v53
	v_cvt_pk_bf16_f32 v4, v4, v5
	v_cvt_pk_bf16_f32 v5, v6, v7
	v_pk_fma_f32 v[6:7], v[36:37], v[48:49], v[38:39] op_sel_hi:[0,1,0]
	v_pk_fma_f32 v[8:9], v[36:37], v[54:55], v[38:39] op_sel_hi:[0,1,0]
	v_cvt_pk_bf16_f32 v6, v6, v7
	v_cvt_pk_bf16_f32 v7, v8, v9
	ds_write_b128 v207, v[10:13]
	ds_write_b128 v213, v[4:7]
	s_waitcnt lgkmcnt(0)
	s_barrier
	ds_read_b64_tr_b16 v[6:7], v167 offset:1024
	ds_read_b64_tr_b16 v[4:5], v165
	ds_read_b64_tr_b16 v[112:113], v165 offset:4096
	ds_read_b64_tr_b16 v[116:117], v165 offset:16384
	ds_read_b64_tr_b16 v[120:121], v165 offset:20480
	ds_read_b64_tr_b16 v[114:115], v167 offset:5120
	ds_read_b64_tr_b16 v[118:119], v167 offset:17408
	ds_read_b64_tr_b16 v[122:123], v167 offset:21504
	s_waitcnt vmcnt(15) lgkmcnt(6)
	v_mfma_f32_32x32x16_bf16 v[48:63], v[4:7], v[0:3], 0
	v_add_u32_e32 v176, v198, v201
	ds_read_b64_tr_b16 v[6:7], v177 offset:1024
	ds_read_b64_tr_b16 v[4:5], v176
	ds_read_b64_tr_b16 v[124:125], v176 offset:4096
	ds_read_b64_tr_b16 v[182:183], v176 offset:16384
	ds_read_b64_tr_b16 v[218:219], v176 offset:20480
	ds_read_b64_tr_b16 v[126:127], v177 offset:5120
	ds_read_b64_tr_b16 v[184:185], v177 offset:17408
	ds_read_b64_tr_b16 v[220:221], v177 offset:21504
	v_add_u32_e32 v179, v199, v202
	v_add_u32_e32 v178, v198, v202
	v_add_u32_e32 v181, v199, v203
	v_add_u32_e32 v180, v198, v203
	s_waitcnt lgkmcnt(6)
	v_mfma_f32_32x32x16_bf16 v[32:47], v[4:7], v[0:3], 0
	ds_read_b64_tr_b16 v[6:7], v179 offset:1024
	ds_read_b64_tr_b16 v[4:5], v178
	ds_read_b64_tr_b16 v[222:223], v178 offset:4096
	ds_read_b64_tr_b16 v[226:227], v178 offset:16384
	ds_read_b64_tr_b16 v[230:231], v178 offset:20480
	ds_read_b64_tr_b16 v[224:225], v179 offset:5120
	ds_read_b64_tr_b16 v[228:229], v179 offset:17408
	ds_read_b64_tr_b16 v[232:233], v179 offset:21504
	s_waitcnt lgkmcnt(6)
	v_mfma_f32_32x32x16_bf16 v[16:31], v[4:7], v[0:3], 0
	ds_read_b64_tr_b16 v[6:7], v181 offset:1024
	ds_read_b64_tr_b16 v[4:5], v180
	ds_read_b64_tr_b16 v[234:235], v180 offset:4096
	ds_read_b64_tr_b16 v[238:239], v180 offset:16384
	ds_read_b64_tr_b16 v[242:243], v180 offset:20480
	ds_read_b64_tr_b16 v[236:237], v181 offset:5120
	ds_read_b64_tr_b16 v[240:241], v181 offset:17408
	ds_read_b64_tr_b16 v[244:245], v181 offset:21504
	s_waitcnt lgkmcnt(6)
	v_mfma_f32_32x32x16_bf16 v[0:15], v[4:7], v[0:3], 0
	s_waitcnt vmcnt(14)
	v_mfma_f32_32x32x16_bf16 v[48:63], v[112:115], v[88:91], v[48:63]
	v_mfma_f32_32x32x16_bf16 v[32:47], v[124:127], v[88:91], v[32:47]
	v_mfma_f32_32x32x16_bf16 v[16:31], v[222:225], v[88:91], v[16:31]
	s_waitcnt lgkmcnt(2)
	v_mfma_f32_32x32x16_bf16 v[0:15], v[234:237], v[88:91], v[0:15]
	s_waitcnt vmcnt(13)
	v_mfma_f32_32x32x16_bf16 v[48:63], v[116:119], v[80:83], v[48:63]
	v_mfma_f32_32x32x16_bf16 v[32:47], v[182:185], v[80:83], v[32:47]
	v_mfma_f32_32x32x16_bf16 v[16:31], v[226:229], v[80:83], v[16:31]
	s_waitcnt lgkmcnt(1)
	v_mfma_f32_32x32x16_bf16 v[0:15], v[238:241], v[80:83], v[0:15]
	v_add_co_u32_e32 v80, vcc, s71, v96
	s_nop 1
	v_addc_co_u32_e32 v81, vcc, 0, v97, vcc
	s_waitcnt vmcnt(12)
	v_mfma_f32_32x32x16_bf16 v[48:63], v[120:123], v[144:147], v[48:63]
	global_load_dwordx4 v[124:127], v[80:81], off nt
	global_load_dwordx4 v[120:123], v[98:99], off nt
	global_load_dwordx4 v[116:119], v[104:105], off nt
	global_load_dwordx4 v[112:115], v[106:107], off nt
	s_nop 0
	global_load_dwordx4 v[104:107], v[168:169], off nt
	global_load_dwordx4 v[96:99], v[170:171], off nt
	global_load_dwordx4 v[88:91], v[172:173], off nt
	global_load_dwordx4 v[80:83], v[174:175], off nt
	v_mfma_f32_32x32x16_bf16 v[32:47], v[218:221], v[144:147], v[32:47]
	v_mfma_f32_32x32x16_bf16 v[16:31], v[230:233], v[144:147], v[16:31]
	s_waitcnt lgkmcnt(0)
	v_mfma_f32_32x32x16_bf16 v[0:15], v[242:245], v[144:147], v[0:15]
	s_and_saveexec_b64 s[0:1], s[4:5]
	s_cbranch_execnz .LBB0_405
	s_or_b64 exec, exec, s[0:1]
	s_and_saveexec_b64 s[0:1], s[4:5]
	s_cbranch_execnz .LBB0_406
